# local seams + D1 seam without L2 writeback + runtime placement check
# speedup vs baseline: 1.0206x; 1.0054x over previous
; template <class T> __device__ __forceinline__ T* as_global(T* p) { return (T*)(GAS T*)p; }
; __device__ __forceinline__ unsigned xb_add(unsigned* p, unsigned v) { return __hip_atomic_fetch_add(p, v, __ATOMIC_RELAXED, __HIP_MEMORY_SCOPE_AGENT); }
; __global__ void __launch_bounds__(NWAVES * 64, 2) fwd_kernel(Args a) {
;     ...
;         if (cu == 0) { unsigned* bw = (unsigned*)(as_global(a.ws) + WS_BAR); for (int i = tid; i < (int)(BAR_BYTES / 4); i += NWAVES * 64) bw[i] = 0u; }
;         grid.sync();
;         if (tid == 0) (void)xb_add(&bar.bar[XB_XCNT(bar.x)], 1u);
.LBB0_185:
	s_or_b64 exec, exec, s[4:5]
	v_cmp_eq_u32_e32 vcc, 0, v210
	s_barrier
	s_and_saveexec_b64 s[4:5], vcc
	s_cbranch_execz .LBB0_189
	s_mov_b64 s[8:9], exec
	v_mbcnt_lo_u32_b32 v0, s8, 0
	v_mbcnt_hi_u32_b32 v0, s9, v0
	v_cmp_eq_u32_e32 vcc, 0, v0
	s_and_saveexec_b64 s[6:7], vcc
	s_cbranch_execz .LBB0_188
	s_and_b32 s3, s2, 7
	s_lshl_b32 s3, s3, 2
	v_mov_b32_e32 v0, s3
	s_lshl_b32 s3, 1, s33
	v_mov_b32_e32 v1, s3
	global_atomic_or v0, v1, s[24:25] offset:64
	s_waitcnt vmcnt(0)
	s_lshl_b32 s3, s33, 8
	s_bcnt1_i32_b64 s8, s[8:9]
	v_mov_b32_e32 v0, s3
	v_mov_b32_e32 v1, s8
	global_atomic_add v0, v1, s[24:25] offset:1024

; __device__ __forceinline__ unsigned xb_ld(unsigned* p)              { return __hip_atomic_load(p, __ATOMIC_RELAXED, __HIP_MEMORY_SCOPE_AGENT); }
; __device__ __forceinline__ void xcd_barrier_complete(unsigned* bar, unsigned x, unsigned& nloc, unsigned& nx) {
;     const unsigned G = gridDim.x * gridDim.y * gridDim.z;
;     unsigned sum, cnt, mine, sp = 0u;
;     for (;;) {
;         sum = 0u; cnt = 0u; mine = 0u;
; #pragma unroll
;         for (unsigned j = 0; j < 16; ++j) { const unsigned c = xb_ld(&bar[XB_XCNT(j)]); sum += c; cnt += (c > 0u) ? 1u : 0u; mine = (j == x) ? c : mine; }
;         if (sum == G) break;
;         __builtin_amdgcn_s_sleep(1);
;         if ((++sp & 255u) == 0u) { if (xb_ld(&bar[XB_TMO])) break; if (sp > XB_SPIN_CAP) { atomicAdd(&bar[XB_TMO], 1u); break; } }
;     }
;     nloc = mine > 0u ? mine : 1u; nx = cnt > 0u ? cnt : 1u;
; }
; __device__ __forceinline__ void xcd_barrier(const XcdBarrier& b) {
;     asm volatile("s_waitcnt vmcnt(0)" ::: "memory");
;     __syncthreads();
;     if (threadIdx.x == 0) {
;         unsigned* bar = b.bar;
;         __builtin_amdgcn_s_waitcnt(0);
;         unsigned nloc = b.st[0], nx = b.st[1];
;         if (nloc == 0u) { xcd_barrier_complete(bar, b.x, nloc, nx); b.st[0] = nloc; b.st[1] = nx; }
.LBB0_403:
	v_readlane_b32 s6, v253, 42
	v_readlane_b32 s7, v253, 43
	v_cmp_ne_u32_e32 vcc, 0, v0
	v_readlane_b32 s5, v254, 5
	v_cndmask_b32_e64 v17, 0, v0, s[6:7]
	v_readlane_b32 s6, v253, 40
	v_readlane_b32 s7, v253, 41
	v_cndmask_b32_e64 v0, 0, 1, vcc
	v_cmp_ne_u32_e32 vcc, 0, v2
	v_cndmask_b32_e64 v17, v17, v2, s[6:7]
	v_readlane_b32 s6, v253, 38
	v_readlane_b32 s7, v253, 39
	v_addc_co_u32_e32 v0, vcc, 0, v0, vcc
	s_nop 0
	v_cndmask_b32_e64 v17, v17, v3, s[6:7]
	v_readlane_b32 s6, v253, 36
	v_readlane_b32 s7, v253, 37
	v_cmp_ne_u32_e32 vcc, 0, v3
	s_nop 0
	v_cndmask_b32_e64 v17, v17, v4, s[6:7]
	v_readlane_b32 s6, v253, 34
	v_readlane_b32 s7, v253, 35
	v_cndmask_b32_e64 v2, 0, 1, vcc
	v_cmp_ne_u32_e32 vcc, 0, v4
	v_cndmask_b32_e64 v17, v17, v5, s[6:7]
	v_readlane_b32 s6, v253, 32
	v_readlane_b32 s7, v253, 33
	v_addc_co_u32_e32 v0, vcc, v0, v2, vcc
	s_nop 0
	v_cndmask_b32_e64 v17, v17, v6, s[6:7]
	v_readlane_b32 s6, v253, 30
	v_readlane_b32 s7, v253, 31
	v_cmp_ne_u32_e32 vcc, 0, v5
	s_nop 0
	v_cndmask_b32_e64 v17, v17, v7, s[6:7]
	v_readlane_b32 s6, v253, 28
	v_readlane_b32 s7, v253, 29
	v_cndmask_b32_e64 v2, 0, 1, vcc
	v_cmp_ne_u32_e32 vcc, 0, v6
	v_cndmask_b32_e64 v17, v17, v8, s[6:7]
	v_readlane_b32 s6, v253, 26
	v_readlane_b32 s7, v253, 27
	v_addc_co_u32_e32 v0, vcc, v0, v2, vcc
	s_nop 0
	v_cndmask_b32_e64 v17, v17, v9, s[6:7]
	v_readlane_b32 s6, v253, 24
	v_cmp_ne_u32_e32 vcc, 0, v7
	v_readlane_b32 s7, v253, 25
	s_nop 0
	v_cndmask_b32_e64 v2, 0, 1, vcc
	v_cmp_ne_u32_e32 vcc, 0, v8
	v_cndmask_b32_e64 v17, v17, v10, s[6:7]
	v_readlane_b32 s6, v253, 22
	v_addc_co_u32_e32 v0, vcc, v0, v2, vcc
	v_readlane_b32 s7, v253, 23
	v_cmp_ne_u32_e32 vcc, 0, v9
	s_nop 0
	v_cndmask_b32_e64 v17, v17, v11, s[6:7]
	v_readlane_b32 s6, v253, 20
	v_cndmask_b32_e64 v2, 0, 1, vcc
	v_cmp_ne_u32_e32 vcc, 0, v10
	v_readlane_b32 s7, v253, 21
	s_nop 0
	v_addc_co_u32_e32 v0, vcc, v0, v2, vcc
	v_cndmask_b32_e64 v17, v17, v12, s[6:7]
	v_readlane_b32 s6, v253, 18
	v_cmp_ne_u32_e32 vcc, 0, v11
	v_readlane_b32 s7, v253, 19
	s_nop 0
	v_cndmask_b32_e64 v2, 0, 1, vcc
	v_cmp_ne_u32_e32 vcc, 0, v12
	v_cndmask_b32_e64 v17, v17, v13, s[6:7]
	v_readlane_b32 s6, v253, 16
	v_addc_co_u32_e32 v0, vcc, v0, v2, vcc
	v_readlane_b32 s7, v253, 17
	v_cmp_ne_u32_e32 vcc, 0, v13
	s_nop 0
	v_cndmask_b32_e64 v17, v17, v14, s[6:7]
	v_readlane_b32 s6, v253, 14
	v_cndmask_b32_e64 v2, 0, 1, vcc
	v_cmp_ne_u32_e32 vcc, 0, v14
	v_readlane_b32 s7, v253, 15
	s_nop 0
	v_addc_co_u32_e32 v0, vcc, v0, v2, vcc
	v_cndmask_b32_e64 v17, v17, v15, s[6:7]
	v_readlane_b32 s6, v253, 12
	v_cmp_ne_u32_e32 vcc, 0, v15
	v_readlane_b32 s7, v253, 13
	s_nop 0
	v_cndmask_b32_e64 v2, 0, 1, vcc
	v_cmp_ne_u32_e32 vcc, 0, v16
	v_cndmask_b32_e64 v17, v17, v16, s[6:7]
	v_max_u32_e32 v3, 1, v17
	v_addc_co_u32_e32 v0, vcc, v0, v2, vcc
	v_max_u32_e32 v2, 1, v0
	v_mov_b32_e32 v0, s5
	v_readlane_b32 s5, v254, 6
	ds_write_b32 v0, v3
	s_nop 0
	v_mov_b32_e32 v0, s5
	ds_write_b32 v0, v2
	v_readlane_b32 s6, v252, 34
	v_readlane_b32 s7, v252, 35
	v_readlane_b32 s5, v252, 0
	s_nop 3
	global_load_dwordx4 v[4:7], v1, s[6:7] offset:-448 sc1
	global_load_dwordx4 v[8:11], v1, s[6:7] offset:-432 sc1
	s_waitcnt vmcnt(0)
	v_or3_b32 v12, v4, v5, v6
	v_or3_b32 v13, v7, v8, v9
	v_or3_b32 v12, v12, v10, v11
	v_or_b32_e32 v12, v12, v13
	v_bcnt_u32_b32 v12, v12, 0
	v_bcnt_u32_b32 v13, v4, 0
	v_bcnt_u32_b32 v13, v5, v13
	v_bcnt_u32_b32 v13, v6, v13
	v_bcnt_u32_b32 v13, v7, v13
	v_bcnt_u32_b32 v13, v8, v13
	v_bcnt_u32_b32 v13, v9, v13
	v_bcnt_u32_b32 v13, v10, v13
	v_bcnt_u32_b32 v13, v11, v13
	v_cmp_eq_u32_e32 vcc, 8, v12
	s_nop 1
	v_cndmask_b32_e64 v12, 0, 1, vcc
	v_cmp_eq_u32_e32 vcc, 8, v13
	s_nop 1
	v_cndmask_b32_e64 v13, 0, 1, vcc
	v_and_b32_e32 v12, v12, v13
	v_and_b32_e32 v12, s5, v12
	v_mov_b32_e32 v13, 0x23084
	ds_write_b32 v13, v12

; __device__ __forceinline__ unsigned xb_ld(unsigned* p)              { return __hip_atomic_load(p, __ATOMIC_RELAXED, __HIP_MEMORY_SCOPE_AGENT); }
; __device__ __forceinline__ unsigned xb_add(unsigned* p, unsigned v) { return __hip_atomic_fetch_add(p, v, __ATOMIC_RELAXED, __HIP_MEMORY_SCOPE_AGENT); }
; #define XB_SPIN(cond, bar) do { unsigned _sp = 0; while (cond) { __builtin_amdgcn_s_sleep(8); \
;     if ((++_sp & 255u) == 0u) { if (xb_ld(&(bar)[XB_TMO])) break; if (_sp > XB_SPIN_CAP) { atomicAdd(&(bar)[XB_TMO], 1u); break; } } } } while (0)
; __device__ __forceinline__ void xcd_barrier(const XcdBarrier& b) {
;     ...
;         if (old + 1u == (gen + 1u) * nloc) {
;             __builtin_amdgcn_fence(__ATOMIC_RELEASE, "agent");
;             asm volatile("s_waitcnt vmcnt(0)" ::: "memory");
;             const unsigned og = xb_add(&bar[XB_TOP], 1u);
;             const unsigned tg = og / nx;
;             if (og + 1u == (tg + 1u) * nx) xb_add(&bar[XB_TOPGEN], 1u);
;             else XB_SPIN(xb_ld(&bar[XB_TOPGEN]) == tg, bar);
.LBB0_420:
	s_andn2_saveexec_b64 s[6:7], s[30:31]
	s_cbranch_execz .LBB0_442
	s_mov_b64 s[30:31], exec
	v_mov_b32_e32 v15, 0x23084
	ds_read_b32 v15, v15
	s_waitcnt lgkmcnt(0)
	v_readfirstlane_b32 s5, v15
	s_nop 3
	s_cmp_lg_u32 s5, 0
	s_cbranch_scc1 .LBB0_439
	buffer_wbl2 sc1
	s_waitcnt lgkmcnt(0)
	s_waitcnt vmcnt(0)
	v_mbcnt_lo_u32_b32 v0, s30, 0
	v_mbcnt_hi_u32_b32 v0, s31, v0
	v_cmp_eq_u32_e32 vcc, 0, v0
	s_and_saveexec_b64 s[42:43], vcc
	s_cbranch_execz .LBB0_423
	s_bcnt1_i32_b64 s5, s[30:31]
	v_readlane_b32 s6, v253, 46
	v_mov_b32_e32 v3, s5
	v_readlane_b32 s7, v253, 47
	s_nop 4
	global_atomic_add v3, v1, v3, s[6:7] sc0

; __device__ __forceinline__ unsigned xb_ld(unsigned* p)              { return __hip_atomic_load(p, __ATOMIC_RELAXED, __HIP_MEMORY_SCOPE_AGENT); }
; __device__ __forceinline__ unsigned xb_add(unsigned* p, unsigned v) { return __hip_atomic_fetch_add(p, v, __ATOMIC_RELAXED, __HIP_MEMORY_SCOPE_AGENT); }
; #define XB_SPIN(cond, bar) do { unsigned _sp = 0; while (cond) { __builtin_amdgcn_s_sleep(8); \
;     if ((++_sp & 255u) == 0u) { if (xb_ld(&(bar)[XB_TMO])) break; if (_sp > XB_SPIN_CAP) { atomicAdd(&(bar)[XB_TMO], 1u); break; } } } } while (0)
; __device__ __forceinline__ void xcd_barrier(const XcdBarrier& b) {
;     ...
;         if (old + 1u == (gen + 1u) * nloc) {
;             __builtin_amdgcn_fence(__ATOMIC_RELEASE, "agent");
;             asm volatile("s_waitcnt vmcnt(0)" ::: "memory");
;             const unsigned og = xb_add(&bar[XB_TOP], 1u);
;             const unsigned tg = og / nx;
;             if (og + 1u == (tg + 1u) * nx) xb_add(&bar[XB_TOPGEN], 1u);
;             else XB_SPIN(xb_ld(&bar[XB_TOPGEN]) == tg, bar);
.LBB0_518:
	s_andn2_saveexec_b64 s[4:5], s[42:43]
	s_cbranch_execz .LBB0_538
	s_mov_b64 s[42:43], exec
	v_mov_b32_e32 v15, 0x23084
	ds_read_b32 v15, v15
	s_waitcnt lgkmcnt(0)
	v_readfirstlane_b32 s5, v15
	s_nop 3
	v_readlane_b32 s4, v252, 23
	s_nop 3
	s_and_b32 s4, s4, s5
	s_cmp_lg_u32 s4, 0
	s_cbranch_scc1 .LBB0_535
	s_cmp_lg_u32 s5, 0
	s_cbranch_scc1 .Ld1_skip_wb
	buffer_wbl2 sc1
.Ld1_skip_wb:
	s_waitcnt lgkmcnt(0)
	s_waitcnt vmcnt(0)
	v_mbcnt_lo_u32_b32 v0, s42, 0
	v_mbcnt_hi_u32_b32 v0, s43, v0
	v_cmp_eq_u32_e32 vcc, 0, v0
	s_and_saveexec_b64 s[44:45], vcc
	s_cbranch_execz .LBB0_521
	s_bcnt1_i32_b64 s4, s[42:43]
	v_mov_b32_e32 v3, s4
	v_readlane_b32 s4, v253, 46
	v_readlane_b32 s5, v253, 47
	s_nop 4
	global_atomic_add v3, v1, v3, s[4:5] sc0

; __device__ __forceinline__ unsigned xb_ld(unsigned* p)              { return __hip_atomic_load(p, __ATOMIC_RELAXED, __HIP_MEMORY_SCOPE_AGENT); }
; __device__ __forceinline__ unsigned xb_add(unsigned* p, unsigned v) { return __hip_atomic_fetch_add(p, v, __ATOMIC_RELAXED, __HIP_MEMORY_SCOPE_AGENT); }
; #define XB_SPIN(cond, bar) do { unsigned _sp = 0; while (cond) { __builtin_amdgcn_s_sleep(8); \
;     if ((++_sp & 255u) == 0u) { if (xb_ld(&(bar)[XB_TMO])) break; if (_sp > XB_SPIN_CAP) { atomicAdd(&(bar)[XB_TMO], 1u); break; } } } } while (0)
; __device__ __forceinline__ void xcd_barrier(const XcdBarrier& b) {
;     ...
;         if (old + 1u == (gen + 1u) * nloc) {
;             __builtin_amdgcn_fence(__ATOMIC_RELEASE, "agent");
;             asm volatile("s_waitcnt vmcnt(0)" ::: "memory");
;             const unsigned og = xb_add(&bar[XB_TOP], 1u);
;             const unsigned tg = og / nx;
;             if (og + 1u == (tg + 1u) * nx) xb_add(&bar[XB_TOPGEN], 1u);
;             else XB_SPIN(xb_ld(&bar[XB_TOPGEN]) == tg, bar);
.LBB0_1258:
	s_mov_b64 s[30:31], exec
	v_mov_b32_e32 v15, 0x23084
	ds_read_b32 v15, v15
	s_waitcnt lgkmcnt(0)
	v_readfirstlane_b32 s4, v15
	s_nop 3
	s_cmp_lg_u32 s4, 0
	s_cbranch_scc1 .LBB0_1274
	buffer_wbl2 sc1
	s_waitcnt lgkmcnt(0)
	s_waitcnt vmcnt(0)
	v_mbcnt_lo_u32_b32 v0, s30, 0
	v_mbcnt_hi_u32_b32 v0, s31, v0
	v_cmp_eq_u32_e32 vcc, 0, v0
	s_and_saveexec_b64 s[42:43], vcc
	s_cbranch_execz .LBB0_1260
	s_bcnt1_i32_b64 s4, s[30:31]
	v_mov_b32_e32 v3, s4
	v_readlane_b32 s4, v253, 46
	v_readlane_b32 s5, v253, 47
	s_nop 4
	global_atomic_add v3, v1, v3, s[4:5] sc0
